# P13 SwiGLU epilogue: the 8 per-row-block ssq2 loads hoisted to the epilogue start (one wait instead of 8 load+store drains)
# speedup vs baseline: 1.0082x; 1.0045x over previous
; __device__ __forceinline__ unsigned pk2(float lo, float hi) { return pg8::cvt_pk_bf16(lo, hi); }
; __device__ __forceinline__ float silu_f(float x) { return x * fast_rcp(1.0f + __expf(-x)); }
;     __device__ __forceinline__ void operator()(AccRef acc, const pg8::Unit& u, int wr, int wc, int fr, int fq) const {
;         const int col = u.pn * 128 + wc * 32 + 8 * fq;
; #pragma unroll
;         for (int ai = 0; ai < 2; ++ai)
; #pragma unroll
;             for (int m = 0; m < 4; ++m) {
;                 const int row = u.pm * 256 + ai * 128 + wr * 64 + m * 16 + fr;
;                 const float s = ssq ? rsqrtf(ssq[row] * (1.0f / 1024.0f) + EPS) : 1.0f;
;                 float h[8];
; #pragma unroll
;                 for (int n = 0; n < 2; ++n)
; #pragma unroll
;                     for (int j = 0; j < 4; ++j) { const float g = acc[ai][0][m][n][j] * s, up = acc[ai][1][m][n][j] * s; h[n * 4 + j] = silu_f(g) * up; }
;                 u32x4 w; w.x = pk2(h[0], h[1]); w.y = pk2(h[2], h[3]); w.z = pk2(h[4], h[5]); w.w = pk2(h[6], h[7]);
;                 *(u32x4*)(O + (size_t)row * DFF + col) = w;
.LBB0_855:
	s_lshl_b32 s23, s40, 8
	v_add_u32_e32 v180, s23, v146
	v_lshlrev_b32_e32 v180, 2, v180
	global_load_dword v172, v180, s[14:15]
	v_add_u32_e32 v180, s23, v148
	v_lshlrev_b32_e32 v180, 2, v180
	global_load_dword v173, v180, s[14:15]
	v_add_u32_e32 v180, s23, v149
	v_lshlrev_b32_e32 v180, 2, v180
	global_load_dword v174, v180, s[14:15]
	v_add_u32_e32 v180, s23, v150
	v_lshlrev_b32_e32 v180, 2, v180
	global_load_dword v175, v180, s[14:15]
	v_add_u32_e32 v180, s23, v146
	v_add_u32_e32 v180, 0x80, v180
	v_lshlrev_b32_e32 v180, 2, v180
	global_load_dword v176, v180, s[14:15]
	v_add_u32_e32 v180, s23, v146
	v_add_u32_e32 v180, 0x90, v180
	v_lshlrev_b32_e32 v180, 2, v180
	global_load_dword v177, v180, s[14:15]
	v_add_u32_e32 v180, s23, v146
	v_add_u32_e32 v180, 0xa0, v180
	v_lshlrev_b32_e32 v180, 2, v180
	global_load_dword v178, v180, s[14:15]
	v_add_u32_e32 v180, s23, v146
	v_add_u32_e32 v180, 0xb0, v180
	v_lshlrev_b32_e32 v180, 2, v180
	global_load_dword v179, v180, s[14:15]
	v_add_u32_e32 v144, s23, v146
	v_ashrrev_i32_e32 v145, 31, v144
	v_lshl_add_u64 v[156:157], v[144:145], 2, s[14:15]
	s_nop 0
	v_lshl_or_b32 v156, s56, 7, v151
	v_ashrrev_i32_e32 v157, 31, v156
	v_mov_b32_e32 v160, v122
	v_mov_b32_e32 v161, v114
	v_mov_b32_e32 v114, v123
	v_lshlrev_b64 v[122:123], 1, v[156:157]
	v_mov_b32_e32 v158, v124
	v_mov_b32_e32 v159, v116
	v_mov_b32_e32 v116, v125
	v_mov_b32_e32 v124, v126
	v_mov_b32_e32 v125, v118
	v_mov_b32_e32 v118, v127
	v_mov_b32_e32 v126, v120
	v_mov_b32_e32 v127, v112
	v_mov_b32_e32 v112, v121
	v_mov_b64_e32 v[120:121], s[12:13]
	v_add_u32_e32 v162, s23, v148
	v_mad_i64_i32 v[164:165], s[42:43], v144, s55, v[120:121]
	v_ashrrev_i32_e32 v163, 31, v162
	s_waitcnt vmcnt(0)
	v_fmamk_f32 v145, v172, 0x3a800000, v155
	v_mul_f32_e32 v156, 0x4b800000, v145
	v_cmp_gt_f32_e32 vcc, s54, v145
	s_nop 1
	v_cndmask_b32_e32 v145, v145, v156, vcc
	v_rsq_f32_e32 v145, v145
	v_lshl_add_u64 v[156:157], v[164:165], 0, v[122:123]
	v_lshl_add_u64 v[164:165], v[162:163], 2, s[14:15]
	v_mul_f32_e32 v163, 0x45800000, v145
	v_cndmask_b32_e32 v166, v145, v163, vcc
	v_pk_mul_f32 v[114:115], v[114:115], v[166:167] op_sel_hi:[1,0]
	v_pk_mul_f32 v[158:159], v[158:159], v[166:167] op_sel_hi:[1,0]
	v_pk_mul_f32 v[116:117], v[116:117], v[166:167] op_sel_hi:[1,0]
	v_pk_mul_f32 v[124:125], v[124:125], v[166:167] op_sel_hi:[1,0]
	v_pk_mul_f32 v[118:119], v[118:119], v[166:167] op_sel_hi:[1,0]
	v_pk_mul_f32 v[126:127], v[126:127], v[166:167] op_sel_hi:[1,0]
	v_pk_mul_f32 v[112:113], v[112:113], v[166:167] op_sel_hi:[1,0]
	v_pk_mul_f32 v[160:161], v[160:161], v[166:167] op_sel_hi:[1,0]
	v_mul_f32_e32 v171, 0xbfb8aa3b, v115
	v_mul_f32_e32 v145, 0xbfb8aa3b, v159
	v_mul_f32_e32 v163, 0xbfb8aa3b, v117
	v_mul_f32_e32 v166, 0xbfb8aa3b, v125
	v_mul_f32_e32 v167, 0xbfb8aa3b, v119
	v_mul_f32_e32 v168, 0xbfb8aa3b, v127
	v_mul_f32_e32 v169, 0xbfb8aa3b, v113
	v_mul_f32_e32 v170, 0xbfb8aa3b, v161
	v_exp_f32_e32 v171, v171
	v_exp_f32_e32 v145, v145
	v_exp_f32_e32 v163, v163
	v_exp_f32_e32 v166, v166
	v_exp_f32_e32 v167, v167
	v_exp_f32_e32 v168, v168
	v_exp_f32_e32 v169, v169
	v_exp_f32_e32 v170, v170
	v_add_f32_e32 v171, 1.0, v171
	v_add_f32_e32 v145, 1.0, v145
	v_add_f32_e32 v163, 1.0, v163
	v_add_f32_e32 v166, 1.0, v166
	v_add_f32_e32 v167, 1.0, v167
	v_add_f32_e32 v168, 1.0, v168
	v_add_f32_e32 v169, 1.0, v169
	v_add_f32_e32 v170, 1.0, v170
	v_rcp_f32_e32 v171, v171
	v_rcp_f32_e32 v145, v145
	v_rcp_f32_e32 v163, v163
	v_rcp_f32_e32 v166, v166
	v_rcp_f32_e32 v167, v167
	v_rcp_f32_e32 v168, v168
	v_rcp_f32_e32 v169, v169
	v_rcp_f32_e32 v170, v170
	v_mul_f32_e32 v115, v115, v171
	v_mul_f32_e32 v145, v159, v145
	v_mul_f32_e32 v117, v117, v163
	v_mul_f32_e32 v125, v125, v166
	v_mul_f32_e32 v119, v119, v167
	v_mul_f32_e32 v127, v127, v168
	v_mul_f32_e32 v113, v113, v169
	v_mul_f32_e32 v159, v161, v170
	v_mul_f32_e32 v115, v114, v115
	v_mul_f32_e32 v145, v158, v145
	v_mul_f32_e32 v116, v116, v117
	v_mul_f32_e32 v117, v124, v125
	v_mul_f32_e32 v118, v118, v119
	v_mul_f32_e32 v119, v126, v127
	v_mul_f32_e32 v124, v112, v113
	v_mul_f32_e32 v125, v160, v159
	v_cvt_pk_bf16_f32 v112, v145, v116
	v_cvt_pk_bf16_f32 v113, v117, v118
	v_cvt_pk_bf16_f32 v114, v119, v124
	v_cvt_pk_bf16_f32 v115, v125, v115
	global_store_dwordx4 v[156:157], v[112:115], off
	s_nop 0
	s_nop 0
	v_mov_b32_e32 v113, v100
	v_mov_b32_e32 v100, v109
	v_mov_b32_e32 v109, v102
	v_mov_b32_e32 v102, v111
	v_mov_b32_e32 v111, v96
	v_mov_b32_e32 v96, v105
	v_mov_b32_e32 v105, v98
	v_mov_b32_e32 v98, v107
	v_mov_b32_e32 v112, v108
	v_mov_b32_e32 v108, v110
	v_mov_b32_e32 v110, v104
	v_mov_b32_e32 v104, v106
	v_add_u32_e32 v106, s23, v149
	v_mad_i64_i32 v[114:115], s[42:43], v162, s55, v[120:121]
	v_lshl_add_u64 v[114:115], v[114:115], 0, v[122:123]
	s_nop 0
	v_fmamk_f32 v107, v173, 0x3a800000, v155
	v_mul_f32_e32 v116, 0x4b800000, v107
	v_cmp_gt_f32_e32 vcc, s54, v107
	s_nop 1
	v_cndmask_b32_e32 v107, v107, v116, vcc
	v_rsq_f32_e32 v118, v107
	v_ashrrev_i32_e32 v107, 31, v106
	v_lshl_add_u64 v[116:117], v[106:107], 2, s[14:15]
	v_mul_f32_e32 v107, 0x45800000, v118
	v_cndmask_b32_e32 v118, v118, v107, vcc
	v_pk_mul_f32 v[98:99], v[98:99], v[118:119] op_sel_hi:[1,0]
	v_pk_mul_f32 v[112:113], v[112:113], v[118:119] op_sel_hi:[1,0]
	v_pk_mul_f32 v[100:101], v[100:101], v[118:119] op_sel_hi:[1,0]
	v_pk_mul_f32 v[108:109], v[108:109], v[118:119] op_sel_hi:[1,0]
	v_pk_mul_f32 v[102:103], v[102:103], v[118:119] op_sel_hi:[1,0]
	v_pk_mul_f32 v[110:111], v[110:111], v[118:119] op_sel_hi:[1,0]
	v_pk_mul_f32 v[96:97], v[96:97], v[118:119] op_sel_hi:[1,0]
	v_pk_mul_f32 v[104:105], v[104:105], v[118:119] op_sel_hi:[1,0]
; __device__ __forceinline__ unsigned pk2(float lo, float hi) { return pg8::cvt_pk_bf16(lo, hi); }
; __device__ __forceinline__ float silu_f(float x) { return x * fast_rcp(1.0f + __expf(-x)); }
;     __device__ __forceinline__ void operator()(AccRef acc, const pg8::Unit& u, int wr, int wc, int fr, int fq) const {
;         const int col = u.pn * 128 + wc * 32 + 8 * fq;
; #pragma unroll
;         for (int ai = 0; ai < 2; ++ai)
; #pragma unroll
;             for (int m = 0; m < 4; ++m) {
;                 const int row = u.pm * 256 + ai * 128 + wr * 64 + m * 16 + fr;
;                 const float s = ssq ? rsqrtf(ssq[row] * (1.0f / 1024.0f) + EPS) : 1.0f;
;                 float h[8];
; #pragma unroll
;                 for (int n = 0; n < 2; ++n)
; #pragma unroll
;                     for (int j = 0; j < 4; ++j) { const float g = acc[ai][0][m][n][j] * s, up = acc[ai][1][m][n][j] * s; h[n * 4 + j] = silu_f(g) * up; }
;                 u32x4 w; w.x = pk2(h[0], h[1]); w.y = pk2(h[2], h[3]); w.z = pk2(h[4], h[5]); w.w = pk2(h[6], h[7]);
;                 *(u32x4*)(O + (size_t)row * DFF + col) = w;
	v_mul_f32_e32 v145, 0xbfb8aa3b, v99
	v_mul_f32_e32 v107, 0xbfb8aa3b, v113
	v_mul_f32_e32 v118, 0xbfb8aa3b, v101
	v_mul_f32_e32 v119, 0xbfb8aa3b, v109
	v_mul_f32_e32 v124, 0xbfb8aa3b, v103
	v_mul_f32_e32 v125, 0xbfb8aa3b, v111
	v_mul_f32_e32 v126, 0xbfb8aa3b, v97
	v_mul_f32_e32 v127, 0xbfb8aa3b, v105
	v_exp_f32_e32 v145, v145
	v_exp_f32_e32 v107, v107
	v_exp_f32_e32 v118, v118
	v_exp_f32_e32 v119, v119
	v_exp_f32_e32 v124, v124
	v_exp_f32_e32 v125, v125
	v_exp_f32_e32 v126, v126
	v_exp_f32_e32 v127, v127
	v_add_f32_e32 v145, 1.0, v145
	v_add_f32_e32 v107, 1.0, v107
	v_add_f32_e32 v118, 1.0, v118
	v_add_f32_e32 v119, 1.0, v119
	v_add_f32_e32 v124, 1.0, v124
	v_add_f32_e32 v125, 1.0, v125
	v_add_f32_e32 v126, 1.0, v126
	v_add_f32_e32 v127, 1.0, v127
	v_rcp_f32_e32 v145, v145
	v_rcp_f32_e32 v107, v107
	v_rcp_f32_e32 v118, v118
	v_rcp_f32_e32 v119, v119
	v_rcp_f32_e32 v124, v124
	v_rcp_f32_e32 v125, v125
	v_rcp_f32_e32 v126, v126
	v_rcp_f32_e32 v127, v127
	v_mul_f32_e32 v99, v99, v145
	v_mul_f32_e32 v107, v113, v107
	v_mul_f32_e32 v101, v101, v118
	v_mul_f32_e32 v109, v109, v119
	v_mul_f32_e32 v103, v103, v124
	v_mul_f32_e32 v111, v111, v125
	v_mul_f32_e32 v97, v97, v126
	v_mul_f32_e32 v105, v105, v127
	v_mul_f32_e32 v99, v98, v99
	v_mul_f32_e32 v107, v112, v107
	v_mul_f32_e32 v100, v100, v101
	v_mul_f32_e32 v101, v108, v109
	v_mul_f32_e32 v102, v102, v103
	v_mul_f32_e32 v103, v110, v111
	v_mul_f32_e32 v108, v96, v97
	v_mul_f32_e32 v104, v104, v105
	v_cvt_pk_bf16_f32 v96, v107, v100
	v_cvt_pk_bf16_f32 v97, v101, v102
	v_cvt_pk_bf16_f32 v98, v103, v108
	v_cvt_pk_bf16_f32 v99, v104, v99
	global_store_dwordx4 v[114:115], v[96:99], off
	s_nop 0
	s_nop 0
	v_mov_b32_e32 v97, v84
	v_mov_b32_e32 v84, v93
	v_mov_b32_e32 v93, v86
	v_mov_b32_e32 v86, v95
	v_mov_b32_e32 v95, v80
	v_mov_b32_e32 v80, v89
	v_mov_b32_e32 v89, v82
	v_mov_b32_e32 v82, v91
	v_mov_b32_e32 v96, v92
	v_mov_b32_e32 v92, v94
	v_mov_b32_e32 v94, v88
	v_mov_b32_e32 v88, v90
	v_add_u32_e32 v90, s23, v150
	v_mad_i64_i32 v[98:99], s[42:43], v106, s55, v[120:121]
	v_lshl_add_u64 v[98:99], v[98:99], 0, v[122:123]
	s_nop 0
	v_fmamk_f32 v91, v174, 0x3a800000, v155
	v_mul_f32_e32 v100, 0x4b800000, v91
	v_cmp_gt_f32_e32 vcc, s54, v91
	s_nop 1
	v_cndmask_b32_e32 v91, v91, v100, vcc
	v_rsq_f32_e32 v102, v91
	v_ashrrev_i32_e32 v91, 31, v90
	v_lshl_add_u64 v[100:101], v[90:91], 2, s[14:15]
	v_mul_f32_e32 v91, 0x45800000, v102
	v_cndmask_b32_e32 v102, v102, v91, vcc
	v_pk_mul_f32 v[82:83], v[82:83], v[102:103] op_sel_hi:[1,0]
	v_pk_mul_f32 v[96:97], v[96:97], v[102:103] op_sel_hi:[1,0]
	v_pk_mul_f32 v[84:85], v[84:85], v[102:103] op_sel_hi:[1,0]
	v_pk_mul_f32 v[92:93], v[92:93], v[102:103] op_sel_hi:[1,0]
	v_pk_mul_f32 v[86:87], v[86:87], v[102:103] op_sel_hi:[1,0]
	v_pk_mul_f32 v[94:95], v[94:95], v[102:103] op_sel_hi:[1,0]
	v_pk_mul_f32 v[80:81], v[80:81], v[102:103] op_sel_hi:[1,0]
	v_pk_mul_f32 v[88:89], v[88:89], v[102:103] op_sel_hi:[1,0]
	v_mul_f32_e32 v108, 0xbfb8aa3b, v83
	v_mul_f32_e32 v91, 0xbfb8aa3b, v97
	v_mul_f32_e32 v102, 0xbfb8aa3b, v85
	v_mul_f32_e32 v103, 0xbfb8aa3b, v93
	v_mul_f32_e32 v104, 0xbfb8aa3b, v87
	v_mul_f32_e32 v105, 0xbfb8aa3b, v95
	v_mul_f32_e32 v106, 0xbfb8aa3b, v81
	v_mul_f32_e32 v107, 0xbfb8aa3b, v89
	v_exp_f32_e32 v108, v108
	v_exp_f32_e32 v91, v91
	v_exp_f32_e32 v102, v102
	v_exp_f32_e32 v103, v103
	v_exp_f32_e32 v104, v104
	v_exp_f32_e32 v105, v105
	v_exp_f32_e32 v106, v106
	v_exp_f32_e32 v107, v107
	v_add_f32_e32 v108, 1.0, v108
	v_add_f32_e32 v91, 1.0, v91
	v_add_f32_e32 v102, 1.0, v102
	v_add_f32_e32 v103, 1.0, v103
	v_add_f32_e32 v104, 1.0, v104
	v_add_f32_e32 v105, 1.0, v105
	v_add_f32_e32 v106, 1.0, v106
	v_add_f32_e32 v107, 1.0, v107
	v_rcp_f32_e32 v108, v108
	v_rcp_f32_e32 v91, v91
	v_rcp_f32_e32 v102, v102
	v_rcp_f32_e32 v103, v103
	v_rcp_f32_e32 v104, v104
	v_rcp_f32_e32 v105, v105
	v_rcp_f32_e32 v106, v106
	v_rcp_f32_e32 v107, v107
	v_mul_f32_e32 v83, v83, v108
	v_mul_f32_e32 v91, v97, v91
	v_mul_f32_e32 v85, v85, v102
	v_mul_f32_e32 v93, v93, v103
	v_mul_f32_e32 v87, v87, v104
	v_mul_f32_e32 v95, v95, v105
	v_mul_f32_e32 v81, v81, v106
	v_mul_f32_e32 v89, v89, v107
	v_mul_f32_e32 v83, v82, v83
	v_mul_f32_e32 v91, v96, v91
	v_mul_f32_e32 v84, v84, v85
	v_mul_f32_e32 v85, v92, v93
	v_mul_f32_e32 v86, v86, v87
	v_mul_f32_e32 v87, v94, v95
	v_mul_f32_e32 v92, v80, v81
	v_mul_f32_e32 v88, v88, v89
	v_cvt_pk_bf16_f32 v80, v91, v84
	v_cvt_pk_bf16_f32 v81, v85, v86
	v_cvt_pk_bf16_f32 v82, v87, v92
	v_cvt_pk_bf16_f32 v83, v88, v83
	global_store_dwordx4 v[98:99], v[80:83], off
	s_nop 0
	s_nop 0
	v_add_u32_e32 v82, 0x80, v144
	v_mov_b32_e32 v81, v68
	v_mov_b32_e32 v68, v77
	v_mov_b32_e32 v77, v70
	v_mov_b32_e32 v70, v79
	v_mov_b32_e32 v79, v64
	v_mov_b32_e32 v64, v73
	v_mov_b32_e32 v73, v66
	v_mov_b32_e32 v66, v75
	v_mov_b32_e32 v80, v76
	v_mov_b32_e32 v76, v78
	v_mov_b32_e32 v78, v72
	v_mov_b32_e32 v72, v74
	v_mad_i64_i32 v[74:75], s[42:43], v90, s55, v[120:121]
	v_lshl_add_u64 v[74:75], v[74:75], 0, v[122:123]
	s_nop 0
	v_fmamk_f32 v83, v175, 0x3a800000, v155
	v_mul_f32_e32 v84, 0x4b800000, v83
	v_cmp_gt_f32_e32 vcc, s54, v83
	s_nop 1
	v_cndmask_b32_e32 v83, v83, v84, vcc
	v_rsq_f32_e32 v86, v83
	v_ashrrev_i32_e32 v83, 31, v82
	v_lshl_add_u64 v[84:85], v[82:83], 2, s[14:15]
	v_mul_f32_e32 v83, 0x45800000, v86
	v_cndmask_b32_e32 v86, v86, v83, vcc
	v_pk_mul_f32 v[66:67], v[66:67], v[86:87] op_sel_hi:[1,0]
	v_pk_mul_f32 v[80:81], v[80:81], v[86:87] op_sel_hi:[1,0]
	v_pk_mul_f32 v[68:69], v[68:69], v[86:87] op_sel_hi:[1,0]
	v_pk_mul_f32 v[76:77], v[76:77], v[86:87] op_sel_hi:[1,0]
	v_pk_mul_f32 v[70:71], v[70:71], v[86:87] op_sel_hi:[1,0]
; __device__ __forceinline__ unsigned pk2(float lo, float hi) { return pg8::cvt_pk_bf16(lo, hi); }
; __device__ __forceinline__ float silu_f(float x) { return x * fast_rcp(1.0f + __expf(-x)); }
;     __device__ __forceinline__ void operator()(AccRef acc, const pg8::Unit& u, int wr, int wc, int fr, int fq) const {
;         const int col = u.pn * 128 + wc * 32 + 8 * fq;
; #pragma unroll
;         for (int ai = 0; ai < 2; ++ai)
; #pragma unroll
;             for (int m = 0; m < 4; ++m) {
;                 const int row = u.pm * 256 + ai * 128 + wr * 64 + m * 16 + fr;
;                 const float s = ssq ? rsqrtf(ssq[row] * (1.0f / 1024.0f) + EPS) : 1.0f;
;                 float h[8];
; #pragma unroll
;                 for (int n = 0; n < 2; ++n)
; #pragma unroll
;                     for (int j = 0; j < 4; ++j) { const float g = acc[ai][0][m][n][j] * s, up = acc[ai][1][m][n][j] * s; h[n * 4 + j] = silu_f(g) * up; }
;                 u32x4 w; w.x = pk2(h[0], h[1]); w.y = pk2(h[2], h[3]); w.z = pk2(h[4], h[5]); w.w = pk2(h[6], h[7]);
;                 *(u32x4*)(O + (size_t)row * DFF + col) = w;
	v_pk_mul_f32 v[78:79], v[78:79], v[86:87] op_sel_hi:[1,0]
	v_pk_mul_f32 v[64:65], v[64:65], v[86:87] op_sel_hi:[1,0]
	v_pk_mul_f32 v[72:73], v[72:73], v[86:87] op_sel_hi:[1,0]
	v_mul_f32_e32 v92, 0xbfb8aa3b, v67
	v_mul_f32_e32 v83, 0xbfb8aa3b, v81
	v_mul_f32_e32 v86, 0xbfb8aa3b, v69
	v_mul_f32_e32 v87, 0xbfb8aa3b, v77
	v_mul_f32_e32 v88, 0xbfb8aa3b, v71
	v_mul_f32_e32 v89, 0xbfb8aa3b, v79
	v_mul_f32_e32 v90, 0xbfb8aa3b, v65
	v_mul_f32_e32 v91, 0xbfb8aa3b, v73
	v_exp_f32_e32 v92, v92
	v_exp_f32_e32 v83, v83
	v_exp_f32_e32 v86, v86
	v_exp_f32_e32 v87, v87
	v_exp_f32_e32 v88, v88
	v_exp_f32_e32 v89, v89
	v_exp_f32_e32 v90, v90
	v_exp_f32_e32 v91, v91
	v_add_f32_e32 v92, 1.0, v92
	v_add_f32_e32 v83, 1.0, v83
	v_add_f32_e32 v86, 1.0, v86
	v_add_f32_e32 v87, 1.0, v87
	v_add_f32_e32 v88, 1.0, v88
	v_add_f32_e32 v89, 1.0, v89
	v_add_f32_e32 v90, 1.0, v90
	v_add_f32_e32 v91, 1.0, v91
	v_rcp_f32_e32 v92, v92
	v_rcp_f32_e32 v83, v83
	v_rcp_f32_e32 v86, v86
	v_rcp_f32_e32 v87, v87
	v_rcp_f32_e32 v88, v88
	v_rcp_f32_e32 v89, v89
	v_rcp_f32_e32 v90, v90
	v_rcp_f32_e32 v91, v91
	v_mul_f32_e32 v67, v67, v92
	v_mul_f32_e32 v81, v81, v83
	v_mul_f32_e32 v69, v69, v86
	v_mul_f32_e32 v77, v77, v87
	v_mul_f32_e32 v71, v71, v88
	v_mul_f32_e32 v79, v79, v89
	v_mul_f32_e32 v65, v65, v90
	v_mul_f32_e32 v73, v73, v91
	v_mul_f32_e32 v67, v66, v67
	v_mul_f32_e32 v80, v80, v81
	v_mul_f32_e32 v68, v68, v69
	v_mul_f32_e32 v69, v76, v77
	v_mul_f32_e32 v70, v70, v71
	v_mul_f32_e32 v71, v78, v79
	v_mul_f32_e32 v76, v64, v65
	v_mul_f32_e32 v72, v72, v73
	v_cvt_pk_bf16_f32 v64, v80, v68
	v_cvt_pk_bf16_f32 v65, v69, v70
	v_cvt_pk_bf16_f32 v66, v71, v76
	v_cvt_pk_bf16_f32 v67, v72, v67
	global_store_dwordx4 v[74:75], v[64:67], off
	s_nop 0
	s_nop 0
	v_mov_b32_e32 v65, v52
	v_mov_b32_e32 v52, v61
	v_mov_b32_e32 v61, v54
	v_mov_b32_e32 v54, v63
	v_mov_b32_e32 v63, v48
	v_mov_b32_e32 v48, v57
	v_mov_b32_e32 v57, v50
	v_mov_b32_e32 v50, v59
	v_mov_b32_e32 v64, v60
	v_mov_b32_e32 v60, v62
	v_mov_b32_e32 v62, v56
	v_mov_b32_e32 v56, v58
	v_add_u32_e32 v58, 0x90, v144
	v_mad_i64_i32 v[66:67], s[42:43], v82, s55, v[120:121]
	v_lshl_add_u64 v[66:67], v[66:67], 0, v[122:123]
	s_nop 0
	v_fmamk_f32 v59, v176, 0x3a800000, v155
	v_mul_f32_e32 v68, 0x4b800000, v59
	v_cmp_gt_f32_e32 vcc, s54, v59
	s_nop 1
	v_cndmask_b32_e32 v59, v59, v68, vcc
	v_rsq_f32_e32 v70, v59
	v_ashrrev_i32_e32 v59, 31, v58
	v_lshl_add_u64 v[68:69], v[58:59], 2, s[14:15]
	v_mul_f32_e32 v59, 0x45800000, v70
	v_cndmask_b32_e32 v70, v70, v59, vcc
	v_pk_mul_f32 v[50:51], v[50:51], v[70:71] op_sel_hi:[1,0]
	v_pk_mul_f32 v[64:65], v[64:65], v[70:71] op_sel_hi:[1,0]
	v_pk_mul_f32 v[52:53], v[52:53], v[70:71] op_sel_hi:[1,0]
	v_pk_mul_f32 v[60:61], v[60:61], v[70:71] op_sel_hi:[1,0]
	v_pk_mul_f32 v[54:55], v[54:55], v[70:71] op_sel_hi:[1,0]
	v_pk_mul_f32 v[62:63], v[62:63], v[70:71] op_sel_hi:[1,0]
	v_pk_mul_f32 v[48:49], v[48:49], v[70:71] op_sel_hi:[1,0]
	v_pk_mul_f32 v[56:57], v[56:57], v[70:71] op_sel_hi:[1,0]
	v_mul_f32_e32 v76, 0xbfb8aa3b, v51
	v_mul_f32_e32 v59, 0xbfb8aa3b, v65
	v_mul_f32_e32 v70, 0xbfb8aa3b, v53
	v_mul_f32_e32 v71, 0xbfb8aa3b, v61
	v_mul_f32_e32 v72, 0xbfb8aa3b, v55
	v_mul_f32_e32 v73, 0xbfb8aa3b, v63
	v_mul_f32_e32 v74, 0xbfb8aa3b, v49
	v_mul_f32_e32 v75, 0xbfb8aa3b, v57
	v_exp_f32_e32 v76, v76
	v_exp_f32_e32 v59, v59
	v_exp_f32_e32 v70, v70
	v_exp_f32_e32 v71, v71
	v_exp_f32_e32 v72, v72
	v_exp_f32_e32 v73, v73
	v_exp_f32_e32 v74, v74
	v_exp_f32_e32 v75, v75
	v_add_f32_e32 v76, 1.0, v76
	v_add_f32_e32 v59, 1.0, v59
	v_add_f32_e32 v70, 1.0, v70
	v_add_f32_e32 v71, 1.0, v71
	v_add_f32_e32 v72, 1.0, v72
	v_add_f32_e32 v73, 1.0, v73
	v_add_f32_e32 v74, 1.0, v74
	v_add_f32_e32 v75, 1.0, v75
	v_rcp_f32_e32 v76, v76
	v_rcp_f32_e32 v59, v59
	v_rcp_f32_e32 v70, v70
	v_rcp_f32_e32 v71, v71
	v_rcp_f32_e32 v72, v72
	v_rcp_f32_e32 v73, v73
	v_rcp_f32_e32 v74, v74
	v_rcp_f32_e32 v75, v75
	v_mul_f32_e32 v51, v51, v76
	v_mul_f32_e32 v59, v65, v59
	v_mul_f32_e32 v53, v53, v70
	v_mul_f32_e32 v61, v61, v71
	v_mul_f32_e32 v55, v55, v72
	v_mul_f32_e32 v63, v63, v73
	v_mul_f32_e32 v49, v49, v74
	v_mul_f32_e32 v57, v57, v75
	v_mul_f32_e32 v51, v50, v51
	v_mul_f32_e32 v59, v64, v59
	v_mul_f32_e32 v52, v52, v53
	v_mul_f32_e32 v53, v60, v61
	v_mul_f32_e32 v54, v54, v55
	v_mul_f32_e32 v55, v62, v63
	v_mul_f32_e32 v60, v48, v49
	v_mul_f32_e32 v56, v56, v57
	v_cvt_pk_bf16_f32 v48, v59, v52
	v_cvt_pk_bf16_f32 v49, v53, v54
	v_cvt_pk_bf16_f32 v50, v55, v60
	v_cvt_pk_bf16_f32 v51, v56, v51
	global_store_dwordx4 v[66:67], v[48:51], off
	s_nop 0
	s_nop 0
	v_mov_b32_e32 v49, v36
	v_mov_b32_e32 v36, v45
	v_mov_b32_e32 v45, v38
	v_mov_b32_e32 v38, v47
	v_mov_b32_e32 v47, v32
	v_mov_b32_e32 v32, v41
	v_mov_b32_e32 v41, v34
	v_mov_b32_e32 v34, v43
	v_mov_b32_e32 v48, v44
	v_mov_b32_e32 v44, v46
	v_mov_b32_e32 v46, v40
	v_mov_b32_e32 v40, v42
	v_add_u32_e32 v42, 0xa0, v144
	v_mad_i64_i32 v[50:51], s[42:43], v58, s55, v[120:121]
	v_lshl_add_u64 v[50:51], v[50:51], 0, v[122:123]
	s_nop 0
	v_fmamk_f32 v43, v177, 0x3a800000, v155
	v_mul_f32_e32 v52, 0x4b800000, v43
	v_cmp_gt_f32_e32 vcc, s54, v43
	s_nop 1
	v_cndmask_b32_e32 v43, v43, v52, vcc
	v_rsq_f32_e32 v54, v43
	v_ashrrev_i32_e32 v43, 31, v42
	v_lshl_add_u64 v[52:53], v[42:43], 2, s[14:15]
	v_mul_f32_e32 v43, 0x45800000, v54
	v_cndmask_b32_e32 v54, v54, v43, vcc
	v_pk_mul_f32 v[34:35], v[34:35], v[54:55] op_sel_hi:[1,0]
	v_pk_mul_f32 v[48:49], v[48:49], v[54:55] op_sel_hi:[1,0]
	v_pk_mul_f32 v[36:37], v[36:37], v[54:55] op_sel_hi:[1,0]
	v_pk_mul_f32 v[44:45], v[44:45], v[54:55] op_sel_hi:[1,0]
	v_pk_mul_f32 v[38:39], v[38:39], v[54:55] op_sel_hi:[1,0]
	v_pk_mul_f32 v[46:47], v[46:47], v[54:55] op_sel_hi:[1,0]
; __device__ __forceinline__ unsigned pk2(float lo, float hi) { return pg8::cvt_pk_bf16(lo, hi); }
; __device__ __forceinline__ float silu_f(float x) { return x * fast_rcp(1.0f + __expf(-x)); }
;     __device__ __forceinline__ void operator()(AccRef acc, const pg8::Unit& u, int wr, int wc, int fr, int fq) const {
;         const int col = u.pn * 128 + wc * 32 + 8 * fq;
; #pragma unroll
;         for (int ai = 0; ai < 2; ++ai)
; #pragma unroll
;             for (int m = 0; m < 4; ++m) {
;                 const int row = u.pm * 256 + ai * 128 + wr * 64 + m * 16 + fr;
;                 const float s = ssq ? rsqrtf(ssq[row] * (1.0f / 1024.0f) + EPS) : 1.0f;
;                 float h[8];
; #pragma unroll
;                 for (int n = 0; n < 2; ++n)
; #pragma unroll
;                     for (int j = 0; j < 4; ++j) { const float g = acc[ai][0][m][n][j] * s, up = acc[ai][1][m][n][j] * s; h[n * 4 + j] = silu_f(g) * up; }
;                 u32x4 w; w.x = pk2(h[0], h[1]); w.y = pk2(h[2], h[3]); w.z = pk2(h[4], h[5]); w.w = pk2(h[6], h[7]);
;                 *(u32x4*)(O + (size_t)row * DFF + col) = w;
	v_pk_mul_f32 v[32:33], v[32:33], v[54:55] op_sel_hi:[1,0]
	v_pk_mul_f32 v[40:41], v[40:41], v[54:55] op_sel_hi:[1,0]
	v_mul_f32_e32 v60, 0xbfb8aa3b, v35
	v_mul_f32_e32 v43, 0xbfb8aa3b, v49
	v_mul_f32_e32 v54, 0xbfb8aa3b, v37
	v_mul_f32_e32 v55, 0xbfb8aa3b, v45
	v_mul_f32_e32 v56, 0xbfb8aa3b, v39
	v_mul_f32_e32 v57, 0xbfb8aa3b, v47
	v_mul_f32_e32 v58, 0xbfb8aa3b, v33
	v_mul_f32_e32 v59, 0xbfb8aa3b, v41
	v_exp_f32_e32 v60, v60
	v_exp_f32_e32 v43, v43
	v_exp_f32_e32 v54, v54
	v_exp_f32_e32 v55, v55
	v_exp_f32_e32 v56, v56
	v_exp_f32_e32 v57, v57
	v_exp_f32_e32 v58, v58
	v_exp_f32_e32 v59, v59
	v_add_f32_e32 v60, 1.0, v60
	v_add_f32_e32 v43, 1.0, v43
	v_add_f32_e32 v54, 1.0, v54
	v_add_f32_e32 v55, 1.0, v55
	v_add_f32_e32 v56, 1.0, v56
	v_add_f32_e32 v57, 1.0, v57
	v_add_f32_e32 v58, 1.0, v58
	v_add_f32_e32 v59, 1.0, v59
	v_rcp_f32_e32 v60, v60
	v_rcp_f32_e32 v43, v43
	v_rcp_f32_e32 v54, v54
	v_rcp_f32_e32 v55, v55
	v_rcp_f32_e32 v56, v56
	v_rcp_f32_e32 v57, v57
	v_rcp_f32_e32 v58, v58
	v_rcp_f32_e32 v59, v59
	v_mul_f32_e32 v35, v35, v60
	v_mul_f32_e32 v43, v49, v43
	v_mul_f32_e32 v37, v37, v54
	v_mul_f32_e32 v45, v45, v55
	v_mul_f32_e32 v39, v39, v56
	v_mul_f32_e32 v47, v47, v57
	v_mul_f32_e32 v33, v33, v58
	v_mul_f32_e32 v41, v41, v59
	v_mul_f32_e32 v35, v34, v35
	v_mul_f32_e32 v43, v48, v43
	v_mul_f32_e32 v36, v36, v37
	v_mul_f32_e32 v37, v44, v45
	v_mul_f32_e32 v38, v38, v39
	v_mul_f32_e32 v39, v46, v47
	v_mul_f32_e32 v44, v32, v33
	v_mul_f32_e32 v40, v40, v41
	v_cvt_pk_bf16_f32 v32, v43, v36
	v_cvt_pk_bf16_f32 v33, v37, v38
	v_cvt_pk_bf16_f32 v34, v39, v44
	v_cvt_pk_bf16_f32 v35, v40, v35
	global_store_dwordx4 v[50:51], v[32:35], off
	s_nop 0
	s_nop 0
	v_mov_b32_e32 v33, v20
	v_mov_b32_e32 v20, v29
	v_mov_b32_e32 v29, v22
	v_mov_b32_e32 v22, v31
	v_mov_b32_e32 v31, v16
	v_mov_b32_e32 v16, v25
	v_mov_b32_e32 v25, v18
	v_mov_b32_e32 v18, v27
	v_mov_b32_e32 v32, v28
	v_mov_b32_e32 v28, v30
	v_mov_b32_e32 v30, v24
	v_mov_b32_e32 v24, v26
	v_add_u32_e32 v26, 0xb0, v144
	v_mad_i64_i32 v[34:35], s[42:43], v42, s55, v[120:121]
	v_lshl_add_u64 v[34:35], v[34:35], 0, v[122:123]
	s_nop 0
	v_fmamk_f32 v27, v178, 0x3a800000, v155
	v_mul_f32_e32 v36, 0x4b800000, v27
	v_cmp_gt_f32_e32 vcc, s54, v27
	s_nop 1
	v_cndmask_b32_e32 v27, v27, v36, vcc
	v_rsq_f32_e32 v38, v27
	v_ashrrev_i32_e32 v27, 31, v26
	v_lshl_add_u64 v[36:37], v[26:27], 2, s[14:15]
	v_mul_f32_e32 v27, 0x45800000, v38
	v_cndmask_b32_e32 v38, v38, v27, vcc
	v_pk_mul_f32 v[18:19], v[18:19], v[38:39] op_sel_hi:[1,0]
	v_pk_mul_f32 v[32:33], v[32:33], v[38:39] op_sel_hi:[1,0]
	v_pk_mul_f32 v[20:21], v[20:21], v[38:39] op_sel_hi:[1,0]
	v_pk_mul_f32 v[28:29], v[28:29], v[38:39] op_sel_hi:[1,0]
	v_pk_mul_f32 v[22:23], v[22:23], v[38:39] op_sel_hi:[1,0]
	v_pk_mul_f32 v[30:31], v[30:31], v[38:39] op_sel_hi:[1,0]
	v_pk_mul_f32 v[16:17], v[16:17], v[38:39] op_sel_hi:[1,0]
	v_pk_mul_f32 v[24:25], v[24:25], v[38:39] op_sel_hi:[1,0]
	v_mul_f32_e32 v44, 0xbfb8aa3b, v19
	v_mul_f32_e32 v27, 0xbfb8aa3b, v33
	v_mul_f32_e32 v38, 0xbfb8aa3b, v21
	v_mul_f32_e32 v39, 0xbfb8aa3b, v29
	v_mul_f32_e32 v40, 0xbfb8aa3b, v23
	v_mul_f32_e32 v41, 0xbfb8aa3b, v31
	v_mul_f32_e32 v42, 0xbfb8aa3b, v17
	v_mul_f32_e32 v43, 0xbfb8aa3b, v25
	v_exp_f32_e32 v44, v44
	v_exp_f32_e32 v27, v27
	v_exp_f32_e32 v38, v38
	v_exp_f32_e32 v39, v39
	v_exp_f32_e32 v40, v40
	v_exp_f32_e32 v41, v41
	v_exp_f32_e32 v42, v42
	v_exp_f32_e32 v43, v43
	v_add_f32_e32 v44, 1.0, v44
	v_add_f32_e32 v27, 1.0, v27
	v_add_f32_e32 v38, 1.0, v38
	v_add_f32_e32 v39, 1.0, v39
	v_add_f32_e32 v40, 1.0, v40
	v_add_f32_e32 v41, 1.0, v41
	v_add_f32_e32 v42, 1.0, v42
	v_add_f32_e32 v43, 1.0, v43
; #define PG8_BAR __builtin_amdgcn_s_barrier()
; __device__ __forceinline__ unsigned pk2(float lo, float hi) { return pg8::cvt_pk_bf16(lo, hi); }
; __device__ __forceinline__ float silu_f(float x) { return x * fast_rcp(1.0f + __expf(-x)); }
; template <class Epi, class Sched, bool ALIGN_EPI = false, bool SP2 = false>
; __device__ __forceinline__ void gemm_phase(PG8_LAS unsigned char* lds, const Gemm g, const Sched& S, const Epi& E) {
;     ...
;         if (!has_next) break;
; #pragma unroll
;         for (int a = 0; a < 2; ++a)
; #pragma unroll
;             for (int b = 0; b < 2; ++b)
; #pragma unroll
;                 for (int m = 0; m < 4; ++m)
; #pragma unroll
;                     for (int n = 0; n < 2; ++n) acc[a][b][m][n] = (f32x4){0.f, 0.f, 0.f, 0.f};
;         cur = nxt; cA = nA; cB = nB; ++ui;
;         if constexpr (ALIGN_EPI) { if (wr == 1) PG8_BAR; }
;     __device__ __forceinline__ void operator()(AccRef acc, const pg8::Unit& u, int wr, int wc, int fr, int fq) const {
;         const int col = u.pn * 128 + wc * 32 + 8 * fq;
; #pragma unroll
;         for (int ai = 0; ai < 2; ++ai)
; #pragma unroll
;             for (int m = 0; m < 4; ++m) {
;                 const int row = u.pm * 256 + ai * 128 + wr * 64 + m * 16 + fr;
;                 const float s = ssq ? rsqrtf(ssq[row] * (1.0f / 1024.0f) + EPS) : 1.0f;
;                 float h[8];
; #pragma unroll
;                 for (int n = 0; n < 2; ++n)
; #pragma unroll
;                     for (int j = 0; j < 4; ++j) { const float g = acc[ai][0][m][n][j] * s, up = acc[ai][1][m][n][j] * s; h[n * 4 + j] = silu_f(g) * up; }
;                 u32x4 w; w.x = pk2(h[0], h[1]); w.y = pk2(h[2], h[3]); w.z = pk2(h[4], h[5]); w.w = pk2(h[6], h[7]);
;                 *(u32x4*)(O + (size_t)row * DFF + col) = w;
	v_rcp_f32_e32 v44, v44
	v_rcp_f32_e32 v27, v27
	v_rcp_f32_e32 v38, v38
	v_rcp_f32_e32 v39, v39
	v_rcp_f32_e32 v40, v40
	v_rcp_f32_e32 v41, v41
	v_rcp_f32_e32 v42, v42
	v_rcp_f32_e32 v43, v43
	v_mul_f32_e32 v19, v19, v44
	v_mul_f32_e32 v27, v33, v27
	v_mul_f32_e32 v21, v21, v38
	v_mul_f32_e32 v29, v29, v39
	v_mul_f32_e32 v23, v23, v40
	v_mul_f32_e32 v31, v31, v41
	v_mul_f32_e32 v17, v17, v42
	v_mul_f32_e32 v25, v25, v43
	v_mul_f32_e32 v19, v18, v19
	v_mul_f32_e32 v27, v32, v27
	v_mul_f32_e32 v20, v20, v21
	v_mul_f32_e32 v21, v28, v29
	v_mul_f32_e32 v22, v22, v23
	v_mul_f32_e32 v23, v30, v31
	v_mul_f32_e32 v28, v16, v17
	v_mul_f32_e32 v24, v24, v25
	v_cvt_pk_bf16_f32 v16, v27, v20
	v_cvt_pk_bf16_f32 v17, v21, v22
	v_cvt_pk_bf16_f32 v18, v23, v28
	v_cvt_pk_bf16_f32 v19, v24, v19
	global_store_dwordx4 v[34:35], v[16:19], off
	s_nop 0
	s_andn2_b64 vcc, exec, s[8:9]
	v_mov_b32_e32 v16, v12
	v_mov_b32_e32 v12, v14
	v_mov_b32_e32 v14, v8
	v_mov_b32_e32 v8, v10
	v_mov_b32_e32 v17, v4
	v_mov_b32_e32 v4, v13
	v_mov_b32_e32 v13, v6
	v_mov_b32_e32 v6, v15
	v_mov_b32_e32 v15, v0
	v_mov_b32_e32 v0, v9
	v_mov_b32_e32 v9, v2
	v_mov_b32_e32 v2, v11
	s_nop 0
	v_fmamk_f32 v10, v179, 0x3a800000, v155
	v_mul_f32_e32 v11, 0x4b800000, v10
	v_cmp_gt_f32_e64 s[8:9], s54, v10
	s_nop 1
	v_cndmask_b32_e64 v10, v10, v11, s[8:9]
	v_rsq_f32_e32 v18, v10
	v_mad_i64_i32 v[10:11], s[42:43], v26, s55, v[120:121]
	v_lshl_add_u64 v[10:11], v[10:11], 0, v[122:123]
	v_mul_f32_e32 v19, 0x45800000, v18
	v_cndmask_b32_e64 v18, v18, v19, s[8:9]
	v_pk_mul_f32 v[2:3], v[2:3], v[18:19] op_sel_hi:[1,0]
	v_pk_mul_f32 v[16:17], v[16:17], v[18:19] op_sel_hi:[1,0]
	v_pk_mul_f32 v[4:5], v[4:5], v[18:19] op_sel_hi:[1,0]
	v_pk_mul_f32 v[12:13], v[12:13], v[18:19] op_sel_hi:[1,0]
	v_pk_mul_f32 v[6:7], v[6:7], v[18:19] op_sel_hi:[1,0]
	v_pk_mul_f32 v[14:15], v[14:15], v[18:19] op_sel_hi:[1,0]
	v_pk_mul_f32 v[0:1], v[0:1], v[18:19] op_sel_hi:[1,0]
	v_pk_mul_f32 v[8:9], v[8:9], v[18:19] op_sel_hi:[1,0]
	v_mul_f32_e32 v25, 0xbfb8aa3b, v3
	v_mul_f32_e32 v18, 0xbfb8aa3b, v17
	v_mul_f32_e32 v19, 0xbfb8aa3b, v5
	v_mul_f32_e32 v20, 0xbfb8aa3b, v13
	v_mul_f32_e32 v21, 0xbfb8aa3b, v7
	v_mul_f32_e32 v22, 0xbfb8aa3b, v15
	v_mul_f32_e32 v23, 0xbfb8aa3b, v1
	v_mul_f32_e32 v24, 0xbfb8aa3b, v9
	v_exp_f32_e32 v25, v25
	v_exp_f32_e32 v18, v18
	v_exp_f32_e32 v19, v19
	v_exp_f32_e32 v20, v20
	v_exp_f32_e32 v21, v21
	v_exp_f32_e32 v22, v22
	v_exp_f32_e32 v23, v23
	v_exp_f32_e32 v24, v24
	v_add_f32_e32 v25, 1.0, v25
	v_add_f32_e32 v18, 1.0, v18
	v_add_f32_e32 v19, 1.0, v19
	v_add_f32_e32 v20, 1.0, v20
	v_add_f32_e32 v21, 1.0, v21
	v_add_f32_e32 v22, 1.0, v22
	v_add_f32_e32 v23, 1.0, v23
	v_add_f32_e32 v24, 1.0, v24
	v_rcp_f32_e32 v25, v25
	v_rcp_f32_e32 v18, v18
	v_rcp_f32_e32 v19, v19
	v_rcp_f32_e32 v20, v20
	v_rcp_f32_e32 v21, v21
	v_rcp_f32_e32 v22, v22
	v_rcp_f32_e32 v23, v23
	v_rcp_f32_e32 v24, v24
	v_mul_f32_e32 v3, v3, v25
	v_mul_f32_e32 v17, v17, v18
	v_mul_f32_e32 v5, v5, v19
	v_mul_f32_e32 v13, v13, v20
	v_mul_f32_e32 v7, v7, v21
	v_mul_f32_e32 v15, v15, v22
	v_mul_f32_e32 v1, v1, v23
	v_mul_f32_e32 v9, v9, v24
	v_mul_f32_e32 v3, v2, v3
	s_mov_b64 s[8:9], -1
	v_mul_f32_e32 v16, v16, v17
	v_mul_f32_e32 v4, v4, v5
	v_mul_f32_e32 v5, v12, v13
	v_mul_f32_e32 v6, v6, v7
	v_mul_f32_e32 v7, v14, v15
	v_mul_f32_e32 v12, v0, v1
	v_mul_f32_e32 v8, v8, v9
	v_cvt_pk_bf16_f32 v0, v16, v4
	v_cvt_pk_bf16_f32 v1, v5, v6
	v_cvt_pk_bf16_f32 v2, v7, v12
	v_cvt_pk_bf16_f32 v3, v8, v3
	global_store_dwordx4 v[10:11], v[0:3], off
	s_cbranch_vccnz .LBB0_847
	s_andn2_b64 vcc, exec, s[10:11]
	s_cbranch_vccnz .LBB0_846
	s_barrier
	s_branch .LBB0_846
